# P2 conv: second grid-stride round spread over all 256 workgroups (256 items each) instead of workgroups 0..127 only
# speedup vs baseline: 1.0090x; 1.0007x over previous
.LBB0_477:
	s_and_b64 s[4:5], s[4:5], s[6:7]
	s_andn2_b64 vcc, exec, s[4:5]
	s_cbranch_vccnz .LBB0_495
	s_waitcnt vmcnt(0)
	v_mov_b32_e32 v1, v254
	v_mov_b32_e32 v0, s0
	v_mov_b32_e32 v2, s0
	v_mov_b32_e32 v3, s1
	v_mov_b32_e32 v4, s1
	v_lshl_add_u32 v109, s2, 9, v1
	s_mov_b32 s3, 0x30000
	v_cmp_gt_i32_e32 vcc, s3, v109
	v_readfirstlane_b32 s10, v2
	v_readfirstlane_b32 s11, v4
	v_readfirstlane_b32 s12, v0
	v_readfirstlane_b32 s13, v3
	s_and_saveexec_b64 s[4:5], vcc
	s_cbranch_execz .LBB0_487
	s_load_dwordx2 s[6:7], s[10:11], 0x48
	s_load_dwordx2 s[8:9], s[12:13], 0x50
	s_waitcnt lgkmcnt(0)
	s_lshl_b32 s3, s33, 9
	v_lshlrev_b32_e32 v108, 3, v109
	s_lshl_b32 s20, s33, 12
	s_cmp_eq_u32 s33, 0x100
	s_cselect_b32 s98, s2, 0
	s_cselect_b32 s99, 0x100, 0
	s_lshl_b32 s98, s98, 8
	s_sub_i32 s3, s3, s98
	s_lshl_b32 s98, s98, 3
	s_sub_i32 s20, s20, s98
	s_mov_b64 s[10:11], 0
	s_mov_b32 s21, 0x2aaaaaab
	s_movk_i32 s22, 0xfd00
	s_mov_b64 s[12:13], 0x1800
	s_movk_i32 s23, 0x1000
	s_mov_b64 s[14:15], 0x2400
	s_movk_i32 s24, 0x600
	s_mov_b32 s25, 0xe000000
	s_brev_b32 s26, 40
	s_mov_b32 s27, 0x2ffff
	v_mov_b32_e32 v132, 0
	s_branch .LBB0_481
.LBB0_480:
	s_or_b64 exec, exec, s[18:19]
	v_mov_b32_e32 v34, s0
	v_mov_b32_e32 v35, s1
	v_lshlrev_b64 v[110:111], 1, v[32:33]
	v_readfirstlane_b32 s16, v34
	v_readfirstlane_b32 s17, v35
	s_load_dwordx2 s[16:17], s[16:17], 0xc0
	v_or_b32_e32 v150, 1, v149
	v_or_b32_e32 v148, 2, v149
	v_or_b32_e32 v147, 3, v149
	v_or_b32_e32 v146, 4, v149
	s_waitcnt lgkmcnt(0)
	v_mov_b64_e32 v[34:35], s[16:17]
	v_mad_i64_i32 v[34:35], s[16:17], v149, s24, v[34:35]
	v_lshl_add_u64 v[32:33], v[34:35], 0, v[110:111]
	v_add_co_u32_e32 v32, vcc, s25, v32
	v_or_b32_e32 v145, 5, v149
	s_nop 0
	v_addc_co_u32_e32 v33, vcc, 0, v33, vcc
	global_load_dwordx4 v[104:107], v[32:33], off
	v_mov_b32_e32 v32, s0
	v_mov_b32_e32 v33, s1
	v_or_b32_e32 v144, 6, v149
	v_readfirstlane_b32 s16, v32
	v_readfirstlane_b32 s17, v33
	s_load_dwordx2 s[16:17], s[16:17], 0xc0
	v_or_b32_e32 v143, 7, v149
	v_or_b32_e32 v142, 8, v149
	v_or_b32_e32 v141, 9, v149
	v_or_b32_e32 v140, 10, v149
	s_waitcnt lgkmcnt(0)
	v_mov_b64_e32 v[32:33], s[16:17]
	v_mad_i64_i32 v[32:33], s[16:17], v150, s24, v[32:33]
	v_lshl_add_u64 v[32:33], v[32:33], 0, v[110:111]
	v_add_co_u32_e32 v32, vcc, s25, v32
	s_waitcnt vmcnt(1)
	v_lshlrev_b32_e32 v117, 16, v28
	v_addc_co_u32_e32 v33, vcc, 0, v33, vcc
	global_load_dwordx4 v[84:87], v[32:33], off
	v_mov_b32_e32 v32, s0
	v_mov_b32_e32 v33, s1
	v_and_b32_e32 v125, 0xffff0000, v28
	v_readfirstlane_b32 s16, v32
	v_readfirstlane_b32 s17, v33
	s_load_dwordx2 s[16:17], s[16:17], 0xc0
	v_lshlrev_b32_e32 v121, 16, v29
	v_and_b32_e32 v119, 0xffff0000, v29
	v_or_b32_e32 v139, 11, v149
	v_lshlrev_b32_e32 v116, 16, v24
	s_waitcnt lgkmcnt(0)
	v_mov_b64_e32 v[32:33], s[16:17]
	v_mad_i64_i32 v[32:33], s[16:17], v148, s24, v[32:33]
	v_lshl_add_u64 v[32:33], v[32:33], 0, v[110:111]
	v_add_co_u32_e32 v32, vcc, s25, v32
	v_mov_b32_e32 v112, v96
	s_nop 0
	v_addc_co_u32_e32 v33, vcc, 0, v33, vcc
	global_load_dwordx4 v[88:91], v[32:33], off
	v_mov_b32_e32 v32, s0
	v_mov_b32_e32 v33, s1
	v_mov_b32_e32 v113, v12
	v_readfirstlane_b32 s16, v32
	v_readfirstlane_b32 s17, v33
	s_load_dwordx2 s[16:17], s[16:17], 0xc0
	v_pk_mul_f32 v[114:115], v[112:113], v[116:117]
	v_lshlrev_b32_e32 v152, 16, v100
	v_add_f32_e32 v12, v20, v114
	v_add_f32_e32 v12, v12, v115
	s_waitcnt lgkmcnt(0)
	v_mov_b64_e32 v[32:33], s[16:17]
	v_mad_i64_i32 v[32:33], s[16:17], v147, s24, v[32:33]
	v_lshl_add_u64 v[32:33], v[32:33], 0, v[110:111]
	v_add_co_u32_e32 v32, vcc, s25, v32
	v_mov_b32_e32 v114, v92
	s_nop 0
	v_addc_co_u32_e32 v33, vcc, 0, v33, vcc
	global_load_dwordx4 v[68:71], v[32:33], off
	v_mov_b32_e32 v32, s0
	v_mov_b32_e32 v33, s1
	v_mov_b32_e32 v115, v16
	v_readfirstlane_b32 s16, v32
	v_readfirstlane_b32 s17, v33
	s_load_dwordx2 s[16:17], s[16:17], 0xc0
	v_and_b32_e32 v124, 0xffff0000, v24
	v_or_b32_e32 v138, 12, v149
	v_lshlrev_b32_e32 v120, 16, v25
	v_lshlrev_b32_e32 v156, 16, v101
	s_waitcnt lgkmcnt(0)
	v_mov_b64_e32 v[32:33], s[16:17]
	v_mad_i64_i32 v[32:33], s[16:17], v146, s24, v[32:33]
	v_lshl_add_u64 v[32:33], v[32:33], 0, v[110:111]
	v_add_co_u32_e32 v32, vcc, s25, v32
	s_waitcnt vmcnt(3)
	v_lshlrev_b32_e32 v153, 16, v104
	v_addc_co_u32_e32 v33, vcc, 0, v33, vcc
	global_load_dwordx4 v[72:75], v[32:33], off
	v_mov_b32_e32 v32, s0
	v_mov_b32_e32 v33, s1
	v_pk_mul_f32 v[154:155], v[114:115], v[152:153]
	v_readfirstlane_b32 s16, v32
	v_readfirstlane_b32 s17, v33
	s_load_dwordx2 s[16:17], s[16:17], 0xc0
	v_add_f32_e32 v12, v12, v154
	v_add_f32_e32 v116, v12, v155
	v_mov_b32_e32 v12, v97
	v_pk_mul_f32 v[96:97], v[12:13], v[124:125]
	s_waitcnt lgkmcnt(0)
	v_mov_b64_e32 v[32:33], s[16:17]
	v_mad_i64_i32 v[32:33], s[16:17], v145, s24, v[32:33]
	v_lshl_add_u64 v[32:33], v[32:33], 0, v[110:111]
	v_add_co_u32_e32 v32, vcc, s25, v32
	v_add_f32_e32 v16, v21, v96
	s_nop 0
	v_addc_co_u32_e32 v33, vcc, 0, v33, vcc
	global_load_dwordx4 v[60:63], v[32:33], off
	v_mov_b32_e32 v32, s0
	v_mov_b32_e32 v33, s1
	v_add_f32_e32 v96, v16, v97
	v_readfirstlane_b32 s16, v32
	v_readfirstlane_b32 s17, v33
	s_load_dwordx2 s[16:17], s[16:17], 0xc0
	v_and_b32_e32 v155, 0xffff0000, v104
	v_and_b32_e32 v154, 0xffff0000, v100
	v_mov_b32_e32 v16, v93
	v_pk_mul_f32 v[92:93], v[16:17], v[154:155]
	s_waitcnt lgkmcnt(0)
	v_mov_b64_e32 v[32:33], s[16:17]
	v_mad_i64_i32 v[32:33], s[16:17], v144, s24, v[32:33]
	v_lshl_add_u64 v[32:33], v[32:33], 0, v[110:111]
	v_add_co_u32_e32 v32, vcc, s25, v32
	v_add_f32_e32 v92, v96, v92
	s_nop 0
	v_addc_co_u32_e32 v33, vcc, 0, v33, vcc
	global_load_dwordx4 v[64:67], v[32:33], off
	v_mov_b32_e32 v32, s0
	v_mov_b32_e32 v33, s1
	v_add_f32_e32 v124, v92, v93
	v_readfirstlane_b32 s16, v32
	v_readfirstlane_b32 s17, v33
	s_load_dwordx2 s[16:17], s[16:17], 0xc0
	v_mov_b32_e32 v92, v98
	v_mov_b32_e32 v93, v14
	v_pk_mul_f32 v[96:97], v[92:93], v[120:121]
	v_lshlrev_b32_e32 v157, 16, v105
	s_waitcnt lgkmcnt(0)
	v_mov_b64_e32 v[32:33], s[16:17]
	v_mad_i64_i32 v[32:33], s[16:17], v143, s24, v[32:33]
	v_lshl_add_u64 v[32:33], v[32:33], 0, v[110:111]
	v_add_co_u32_e32 v32, vcc, s25, v32
	v_add_f32_e32 v14, v22, v96
	s_nop 0
	v_addc_co_u32_e32 v33, vcc, 0, v33, vcc
	global_load_dwordx4 v[52:55], v[32:33], off
	v_mov_b32_e32 v32, s0
	v_mov_b32_e32 v33, s1
	v_add_f32_e32 v14, v14, v97
	v_readfirstlane_b32 s16, v32
	v_readfirstlane_b32 s17, v33
	s_load_dwordx2 s[16:17], s[16:17], 0xc0
	v_mov_b32_e32 v96, v94
	v_mov_b32_e32 v97, v18
	v_pk_mul_f32 v[158:159], v[96:97], v[156:157]
	v_and_b32_e32 v118, 0xffff0000, v25
	s_waitcnt lgkmcnt(0)
	v_mov_b64_e32 v[32:33], s[16:17]
	v_mad_i64_i32 v[32:33], s[16:17], v142, s24, v[32:33]
	v_lshl_add_u64 v[32:33], v[32:33], 0, v[110:111]
	v_add_co_u32_e32 v32, vcc, s25, v32
	v_add_f32_e32 v14, v14, v158
	s_nop 0
	v_addc_co_u32_e32 v33, vcc, 0, v33, vcc
	global_load_dwordx4 v[56:59], v[32:33], off
	v_mov_b32_e32 v32, s0
	v_mov_b32_e32 v33, s1
	v_add_f32_e32 v120, v14, v159
	v_readfirstlane_b32 s16, v32
	v_readfirstlane_b32 s17, v33
	s_load_dwordx2 s[16:17], s[16:17], 0xc0
	v_mov_b32_e32 v14, v99
	v_pk_mul_f32 v[98:99], v[14:15], v[118:119]
	v_or_b32_e32 v137, 13, v149
	v_add_f32_e32 v18, v23, v98
	s_waitcnt lgkmcnt(0)
	v_mov_b64_e32 v[32:33], s[16:17]
	v_mad_i64_i32 v[32:33], s[16:17], v141, s24, v[32:33]
	v_lshl_add_u64 v[32:33], v[32:33], 0, v[110:111]
	v_add_co_u32_e32 v32, vcc, s25, v32
	v_add_f32_e32 v98, v18, v99
	s_nop 0
	v_addc_co_u32_e32 v33, vcc, 0, v33, vcc
	global_load_dwordx4 v[44:47], v[32:33], off
	v_mov_b32_e32 v32, s0
	v_mov_b32_e32 v33, s1
	v_and_b32_e32 v105, 0xffff0000, v105
	v_readfirstlane_b32 s16, v32
	v_readfirstlane_b32 s17, v33
	s_load_dwordx2 s[16:17], s[16:17], 0xc0
	v_and_b32_e32 v104, 0xffff0000, v101
	v_mov_b32_e32 v18, v95
	v_pk_mul_f32 v[94:95], v[18:19], v[104:105]
	v_lshlrev_b32_e32 v129, 16, v30
	s_waitcnt lgkmcnt(0)
	v_mov_b64_e32 v[32:33], s[16:17]
	v_mad_i64_i32 v[32:33], s[16:17], v140, s24, v[32:33]
	v_lshl_add_u64 v[32:33], v[32:33], 0, v[110:111]
	v_add_co_u32_e32 v32, vcc, s25, v32
	v_add_f32_e32 v94, v98, v94
	s_nop 0
	v_addc_co_u32_e32 v33, vcc, 0, v33, vcc
	global_load_dwordx4 v[48:51], v[32:33], off
	v_mov_b32_e32 v32, s0
	v_mov_b32_e32 v33, s1
	v_lshlrev_b32_e32 v128, 16, v26
	v_readfirstlane_b32 s16, v32
	v_readfirstlane_b32 s17, v33
	s_load_dwordx2 s[16:17], s[16:17], 0xc0
	v_add_f32_e32 v118, v94, v95
	v_mov_b32_e32 v94, v80
	v_mov_b32_e32 v95, v0
	v_mov_b32_e32 v24, s0
	s_waitcnt lgkmcnt(0)
	v_mov_b64_e32 v[28:29], s[16:17]
	v_mad_i64_i32 v[28:29], s[16:17], v139, s24, v[28:29]
	v_lshl_add_u64 v[28:29], v[28:29], 0, v[110:111]
	v_add_co_u32_e32 v28, vcc, s25, v28
	v_mov_b32_e32 v32, s1
	s_nop 0
	v_addc_co_u32_e32 v29, vcc, 0, v29, vcc
	global_load_dwordx4 v[36:39], v[28:29], off
	v_mov_b32_e32 v28, s0
	v_mov_b32_e32 v29, s1
	v_pk_mul_f32 v[98:99], v[94:95], v[128:129]
	v_readfirstlane_b32 s16, v28
	v_readfirstlane_b32 s17, v29
	s_load_dwordx2 s[16:17], s[16:17], 0xc0
	v_and_b32_e32 v127, 0xffff0000, v30
	v_lshlrev_b32_e32 v123, 16, v31
	v_and_b32_e32 v131, 0xffff0000, v31
	v_add_f32_e32 v0, v8, v98
	s_waitcnt lgkmcnt(0)
	v_mov_b64_e32 v[28:29], s[16:17]
	v_mad_i64_i32 v[28:29], s[16:17], v138, s24, v[28:29]
	v_lshl_add_u64 v[28:29], v[28:29], 0, v[110:111]
	v_add_co_u32_e32 v28, vcc, s25, v28
	v_add_f32_e32 v0, v0, v99
	s_nop 0
	v_addc_co_u32_e32 v29, vcc, 0, v29, vcc
	global_load_dwordx4 v[40:43], v[28:29], off
	v_mov_b32_e32 v28, s0
	v_mov_b32_e32 v29, s1
	v_lshlrev_b32_e32 v159, 16, v106
	v_readfirstlane_b32 s16, v28
	v_readfirstlane_b32 s17, v29
	s_load_dwordx2 s[16:17], s[16:17], 0xc0
	v_lshlrev_b32_e32 v158, 16, v102
	v_mov_b32_e32 v98, v76
	v_mov_b32_e32 v99, v4
	v_pk_mul_f32 v[100:101], v[98:99], v[158:159]
	s_waitcnt lgkmcnt(0)
	v_mov_b64_e32 v[28:29], s[16:17]
	v_mad_i64_i32 v[28:29], s[16:17], v137, s24, v[28:29]
	v_lshl_add_u64 v[28:29], v[28:29], 0, v[110:111]
	v_add_co_u32_e32 v28, vcc, s25, v28
	v_add_f32_e32 v0, v0, v100
	s_nop 0
	v_addc_co_u32_e32 v29, vcc, 0, v29, vcc
	global_load_dwordx4 v[28:31], v[28:29], off
	v_and_b32_e32 v126, 0xffff0000, v26
	v_readfirstlane_b32 s16, v24
	v_readfirstlane_b32 s17, v32
	s_load_dwordx2 s[16:17], s[16:17], 0xc0
	v_add_f32_e32 v128, v0, v101
	v_mov_b32_e32 v0, v81
	v_pk_mul_f32 v[80:81], v[0:1], v[126:127]
	v_or_b32_e32 v136, 14, v149
	s_waitcnt lgkmcnt(0)
	v_mov_b64_e32 v[24:25], s[16:17]
	v_add_f32_e32 v4, v9, v80
	v_mad_i64_i32 v[24:25], s[16:17], v136, s24, v[24:25]
	v_add_f32_e32 v80, v4, v81
	v_and_b32_e32 v161, 0xffff0000, v106
	v_and_b32_e32 v160, 0xffff0000, v102
	v_mov_b32_e32 v4, v77
	v_lshl_add_u64 v[24:25], v[24:25], 0, v[110:111]
	v_pk_mul_f32 v[76:77], v[4:5], v[160:161]
	v_add_co_u32_e32 v24, vcc, s25, v24
	v_add_f32_e32 v76, v80, v76
	s_nop 0
	v_addc_co_u32_e32 v25, vcc, 0, v25, vcc
	v_lshlrev_b32_e32 v122, 16, v27
	v_add_f32_e32 v102, v76, v77
	v_mov_b32_e32 v76, v82
	v_mov_b32_e32 v77, v2
	global_load_dwordx4 v[32:35], v[24:25], off
	v_mov_b32_e32 v24, s0
	v_mov_b32_e32 v25, s1
	v_pk_mul_f32 v[80:81], v[76:77], v[122:123]
	v_lshlrev_b32_e32 v162, 16, v103
	v_readfirstlane_b32 s16, v24
	v_readfirstlane_b32 s17, v25
	v_add_f32_e32 v2, v10, v80
	s_load_dwordx2 s[16:17], s[16:17], 0xc0
	v_add_f32_e32 v2, v2, v81
	v_lshlrev_b32_e32 v163, 16, v107
	v_mov_b32_e32 v80, v78
	v_mov_b32_e32 v81, v6
	v_pk_mul_f32 v[100:101], v[80:81], v[162:163]
	v_and_b32_e32 v130, 0xffff0000, v27
	v_add_f32_e32 v2, v2, v100
	v_add_f32_e32 v122, v2, v101
	v_mov_b32_e32 v2, v83
	v_pk_mul_f32 v[82:83], v[2:3], v[130:131]
	v_or_b32_e32 v135, 15, v149
	s_waitcnt lgkmcnt(0)
	v_mov_b64_e32 v[24:25], s[16:17]
	v_add_f32_e32 v6, v11, v82
	v_mad_i64_i32 v[24:25], s[16:17], v135, s24, v[24:25]
	v_add_f32_e32 v82, v6, v83
	v_and_b32_e32 v107, 0xffff0000, v107
	v_and_b32_e32 v106, 0xffff0000, v103
	v_mov_b32_e32 v6, v79
	v_lshl_add_u64 v[24:25], v[24:25], 0, v[110:111]
	v_pk_mul_f32 v[78:79], v[6:7], v[106:107]
	v_add_co_u32_e32 v24, vcc, s25, v24
	v_add_f32_e32 v78, v82, v78
	s_nop 0
	v_addc_co_u32_e32 v25, vcc, 0, v25, vcc
	v_add_f32_e32 v78, v78, v79
	global_load_dwordx4 v[24:27], v[24:25], off
	v_cvt_pk_bf16_f32 v100, v116, v124
	v_cvt_pk_bf16_f32 v101, v120, v118
	v_cvt_pk_bf16_f32 v102, v128, v102
	v_cvt_pk_bf16_f32 v103, v122, v78
	v_mov_b32_e32 v78, s0
	v_mov_b32_e32 v79, s1
	v_mov_b32_e32 v133, s0
	v_readfirstlane_b32 s16, v78
	v_readfirstlane_b32 s17, v79
	s_load_dwordx2 s[16:17], s[16:17], 0xc0
	v_mov_b32_e32 v134, s1
	v_add_u32_e32 v109, s3, v109
	v_add_u32_e32 v108, s20, v108
	v_and_b32_e32 v242, s99, v254
	v_lshl_or_b32 v109, v242, 12, v109
	s_waitcnt lgkmcnt(0)
	v_mov_b64_e32 v[78:79], s[16:17]
	v_mad_i64_i32 v[78:79], s[16:17], v149, s24, v[78:79]
	v_lshl_add_u64 v[78:79], v[78:79], 0, v[110:111]
	v_add_co_u32_e32 v78, vcc, s26, v78
	s_nop 1
	v_addc_co_u32_e32 v79, vcc, 0, v79, vcc
	global_store_dwordx4 v[78:79], v[100:103], off
	v_mov_b32_e32 v78, v117
	v_mov_b32_e32 v79, v152
	v_pk_mul_f32 v[78:79], v[112:113], v[78:79]
	s_nop 0
	v_add_f32_e32 v78, v20, v78
	v_add_f32_e32 v102, v78, v79
	v_mov_b32_e32 v78, v125
	v_mov_b32_e32 v79, v154
	v_pk_mul_f32 v[78:79], v[12:13], v[78:79]
	s_nop 0
	v_add_f32_e32 v78, v21, v78
	v_add_f32_e32 v118, v78, v79
	v_mov_b32_e32 v78, v121
	v_mov_b32_e32 v79, v156
	v_pk_mul_f32 v[78:79], v[92:93], v[78:79]
	s_nop 0
	v_add_f32_e32 v78, v22, v78
	v_add_f32_e32 v124, v78, v79
	v_mov_b32_e32 v78, v119
	v_mov_b32_e32 v79, v104
	v_pk_mul_f32 v[78:79], v[14:15], v[78:79]
	s_nop 0
	v_add_f32_e32 v78, v23, v78
	v_add_f32_e32 v125, v78, v79
	v_mov_b32_e32 v78, v129
	v_mov_b32_e32 v79, v158
	v_pk_mul_f32 v[78:79], v[94:95], v[78:79]
	s_nop 0
	v_add_f32_e32 v78, v8, v78
	v_add_f32_e32 v126, v78, v79
	v_mov_b32_e32 v78, v127
	v_mov_b32_e32 v79, v160
	v_pk_mul_f32 v[78:79], v[0:1], v[78:79]
	s_nop 0
	v_add_f32_e32 v78, v9, v78
	v_add_f32_e32 v130, v78, v79
	v_mov_b32_e32 v78, v123
	v_mov_b32_e32 v79, v162
	v_pk_mul_f32 v[78:79], v[76:77], v[78:79]
	s_nop 0
	v_add_f32_e32 v78, v10, v78
	v_add_f32_e32 v149, v78, v79
	v_mov_b32_e32 v78, v131
	v_mov_b32_e32 v79, v106
	v_pk_mul_f32 v[78:79], v[2:3], v[78:79]
	s_nop 0
	v_add_f32_e32 v78, v11, v78
	v_add_f32_e32 v151, v78, v79
	v_pk_mul_f32 v[78:79], v[112:113], v[152:153]
	s_nop 0
	v_add_f32_e32 v78, v20, v78
	v_add_f32_e32 v103, v78, v79
	s_waitcnt vmcnt(15)
	v_lshlrev_b32_e32 v78, 16, v84
	s_waitcnt vmcnt(14)
	v_lshlrev_b32_e32 v79, 16, v88
	v_pk_mov_b32 v[100:101], v[152:153], v[78:79] op_sel:[1,0]
	s_nop 0
	v_pk_mul_f32 v[82:83], v[114:115], v[100:101]
	s_nop 0
	v_add_f32_e32 v82, v102, v82
	v_add_f32_e32 v119, v82, v83
	v_pk_mul_f32 v[82:83], v[114:115], v[78:79]
	v_and_b32_e32 v102, 0xffff0000, v84
	v_add_f32_e32 v82, v103, v82
	v_add_f32_e32 v164, v82, v83
	v_pk_mul_f32 v[82:83], v[12:13], v[154:155]
	v_and_b32_e32 v103, 0xffff0000, v88
	v_add_f32_e32 v82, v21, v82
	v_pk_mov_b32 v[116:117], v[154:155], v[102:103] op_sel:[1,0]
	v_add_f32_e32 v120, v82, v83
	v_pk_mul_f32 v[82:83], v[16:17], v[116:117]
	v_and_b32_e32 v88, 0xffff0000, v85
	v_add_f32_e32 v82, v118, v82
	v_add_f32_e32 v82, v82, v83
	v_cvt_pk_bf16_f32 v82, v119, v82
	v_pk_mul_f32 v[118:119], v[16:17], v[102:103]
	s_nop 0
	v_add_f32_e32 v83, v120, v118
	v_add_f32_e32 v165, v83, v119
	v_pk_mul_f32 v[118:119], v[92:93], v[156:157]
	s_nop 0
	v_add_f32_e32 v83, v22, v118
	v_add_f32_e32 v83, v83, v119
	v_lshlrev_b32_e32 v118, 16, v85
	v_lshlrev_b32_e32 v119, 16, v89
	v_pk_mov_b32 v[120:121], v[156:157], v[118:119] op_sel:[1,0]
	v_and_b32_e32 v89, 0xffff0000, v89
	v_pk_mul_f32 v[122:123], v[96:97], v[120:121]
	s_nop 0
	v_add_f32_e32 v84, v124, v122
	v_add_f32_e32 v124, v84, v123
	v_pk_mul_f32 v[122:123], v[96:97], v[118:119]
	s_nop 0
	v_add_f32_e32 v83, v83, v122
	v_add_f32_e32 v166, v83, v123
	v_pk_mul_f32 v[122:123], v[14:15], v[104:105]
	v_pk_mov_b32 v[104:105], v[104:105], v[88:89] op_sel:[1,0]
	v_add_f32_e32 v83, v23, v122
	v_pk_mul_f32 v[84:85], v[18:19], v[104:105]
	v_add_f32_e32 v122, v83, v123
	v_add_f32_e32 v83, v125, v84
	v_add_f32_e32 v83, v83, v85
	v_pk_mul_f32 v[84:85], v[18:19], v[88:89]
	v_lshlrev_b32_e32 v123, 16, v90
	v_add_f32_e32 v84, v122, v84
	v_add_f32_e32 v167, v84, v85
	v_pk_mul_f32 v[84:85], v[94:95], v[158:159]
	v_lshlrev_b32_e32 v122, 16, v86
	v_cvt_pk_bf16_f32 v83, v124, v83
	v_add_f32_e32 v84, v8, v84
	v_pk_mov_b32 v[124:125], v[158:159], v[122:123] op_sel:[1,0]
	v_add_f32_e32 v127, v84, v85
	v_pk_mul_f32 v[84:85], v[98:99], v[124:125]
	s_nop 0
	v_add_f32_e32 v84, v126, v84
	v_add_f32_e32 v131, v84, v85
	v_pk_mul_f32 v[84:85], v[98:99], v[122:123]
	v_and_b32_e32 v126, 0xffff0000, v86
	v_add_f32_e32 v84, v127, v84
	v_add_f32_e32 v158, v84, v85
	v_pk_mul_f32 v[84:85], v[0:1], v[160:161]
	v_and_b32_e32 v127, 0xffff0000, v90
	v_add_f32_e32 v84, v9, v84
	v_pk_mov_b32 v[128:129], v[160:161], v[126:127] op_sel:[1,0]
	v_add_f32_e32 v152, v84, v85
	v_pk_mul_f32 v[84:85], v[4:5], v[128:129]
	v_and_b32_e32 v90, 0xffff0000, v87
	v_add_f32_e32 v84, v130, v84
	v_add_f32_e32 v84, v84, v85
	v_cvt_pk_bf16_f32 v84, v131, v84
	v_pk_mul_f32 v[130:131], v[4:5], v[126:127]
	s_nop 0
	v_add_f32_e32 v85, v152, v130
	v_add_f32_e32 v159, v85, v131
	v_pk_mul_f32 v[130:131], v[76:77], v[162:163]
	s_nop 0
	v_add_f32_e32 v85, v10, v130
	v_add_f32_e32 v85, v85, v131
	v_lshlrev_b32_e32 v130, 16, v87
	v_lshlrev_b32_e32 v131, 16, v91
	v_pk_mov_b32 v[152:153], v[162:163], v[130:131] op_sel:[1,0]
	v_and_b32_e32 v91, 0xffff0000, v91
	v_pk_mul_f32 v[154:155], v[80:81], v[152:153]
	s_nop 0
	v_add_f32_e32 v86, v149, v154
	v_add_f32_e32 v149, v86, v155
	v_pk_mov_b32 v[86:87], v[106:107], v[90:91] op_sel:[1,0]
	v_pk_mul_f32 v[154:155], v[80:81], v[130:131]
	v_pk_mul_f32 v[156:157], v[6:7], v[86:87]
	v_add_f32_e32 v154, v85, v154
	v_add_f32_e32 v85, v151, v156
	v_add_f32_e32 v85, v85, v157
	v_cvt_pk_bf16_f32 v85, v149, v85
	v_mov_b32_e32 v149, s0
	v_mov_b32_e32 v151, s1
	v_pk_mul_f32 v[106:107], v[2:3], v[106:107]
	v_readfirstlane_b32 s16, v149
	v_readfirstlane_b32 s17, v151
	s_load_dwordx2 s[16:17], s[16:17], 0xc0
	v_add_f32_e32 v106, v11, v106
	v_add_f32_e32 v151, v106, v107
	v_add_f32_e32 v149, v154, v155
	s_waitcnt lgkmcnt(0)
	v_mov_b64_e32 v[106:107], s[16:17]
	v_mad_i64_i32 v[106:107], s[16:17], v150, s24, v[106:107]
	v_lshl_add_u64 v[106:107], v[106:107], 0, v[110:111]
	v_add_co_u32_e32 v106, vcc, s26, v106
	s_nop 1
	v_addc_co_u32_e32 v107, vcc, 0, v107, vcc
	global_store_dwordx4 v[106:107], v[82:85], off
	v_mov_b32_e32 v106, s0
	v_mov_b32_e32 v107, s1
	v_pk_mul_f32 v[82:83], v[6:7], v[90:91]
	s_nop 0
	v_add_f32_e32 v82, v151, v82
	v_add_f32_e32 v85, v82, v83
	v_cvt_pk_bf16_f32 v82, v164, v165
	v_cvt_pk_bf16_f32 v83, v166, v167
	v_cvt_pk_bf16_f32 v84, v158, v159
	v_cvt_pk_bf16_f32 v85, v149, v85
	s_nop 0
	v_readfirstlane_b32 s16, v106
	v_readfirstlane_b32 s17, v107
	s_load_dwordx2 s[16:17], s[16:17], 0xc0
	s_waitcnt lgkmcnt(0)
	v_mov_b64_e32 v[106:107], s[16:17]
	v_mad_i64_i32 v[106:107], s[16:17], v148, s24, v[106:107]
	v_lshl_add_u64 v[106:107], v[106:107], 0, v[110:111]
	v_add_co_u32_e32 v106, vcc, s26, v106
	s_nop 1
	v_addc_co_u32_e32 v107, vcc, 0, v107, vcc
	global_store_dwordx4 v[106:107], v[82:85], off
	s_nop 1
	v_pk_mul_f32 v[82:83], v[112:113], v[100:101]
	s_nop 0
	v_add_f32_e32 v82, v20, v82
	v_add_f32_e32 v100, v82, v83
	v_pk_mul_f32 v[82:83], v[12:13], v[116:117]
	s_nop 0
	v_add_f32_e32 v82, v21, v82
	v_add_f32_e32 v106, v82, v83
	v_pk_mul_f32 v[82:83], v[92:93], v[120:121]
	s_nop 0
	v_add_f32_e32 v82, v22, v82
	v_add_f32_e32 v107, v82, v83
	v_pk_mul_f32 v[82:83], v[14:15], v[104:105]
	s_nop 0
	v_add_f32_e32 v82, v23, v82
	v_add_f32_e32 v116, v82, v83
	v_pk_mul_f32 v[82:83], v[94:95], v[124:125]
	s_nop 0
	v_add_f32_e32 v82, v8, v82
	v_add_f32_e32 v120, v82, v83
	v_pk_mul_f32 v[82:83], v[0:1], v[128:129]
	s_nop 0
	v_add_f32_e32 v82, v9, v82
	v_add_f32_e32 v124, v82, v83
	v_pk_mul_f32 v[82:83], v[76:77], v[152:153]
	s_nop 0
	v_add_f32_e32 v82, v10, v82
	v_add_f32_e32 v128, v82, v83
	v_pk_mul_f32 v[82:83], v[2:3], v[86:87]
	s_nop 0
	v_add_f32_e32 v82, v11, v82
	v_add_f32_e32 v148, v82, v83
	v_pk_mul_f32 v[82:83], v[112:113], v[78:79]
	s_nop 0
	v_add_f32_e32 v82, v20, v82
	v_add_f32_e32 v86, v82, v83
	s_waitcnt vmcnt(15)
	v_lshlrev_b32_e32 v82, 16, v68
	s_waitcnt vmcnt(14)
	v_lshlrev_b32_e32 v83, 16, v72
	v_pk_mov_b32 v[78:79], v[78:79], v[82:83] op_sel:[1,0]
	s_nop 0
	v_pk_mul_f32 v[84:85], v[114:115], v[78:79]
	s_nop 0
	v_add_f32_e32 v84, v100, v84
	v_add_f32_e32 v104, v84, v85
	v_pk_mul_f32 v[84:85], v[114:115], v[82:83]
	s_nop 0
	v_add_f32_e32 v84, v86, v84
	v_add_f32_e32 v149, v84, v85
	v_pk_mul_f32 v[84:85], v[12:13], v[102:103]
	s_nop 0
	v_add_f32_e32 v84, v21, v84
	v_add_f32_e32 v105, v84, v85
	v_and_b32_e32 v85, 0xffff0000, v72
	v_and_b32_e32 v84, 0xffff0000, v68
	v_pk_mov_b32 v[86:87], v[102:103], v[84:85] op_sel:[1,0]
	s_nop 0
	v_pk_mul_f32 v[100:101], v[16:17], v[86:87]
	s_nop 0
	v_add_f32_e32 v68, v106, v100
	v_add_f32_e32 v68, v68, v101
	v_pk_mul_f32 v[100:101], v[16:17], v[84:85]
	v_cvt_pk_bf16_f32 v68, v104, v68
	s_nop 0
	v_add_f32_e32 v72, v105, v100
	v_add_f32_e32 v150, v72, v101
	v_pk_mul_f32 v[100:101], v[92:93], v[118:119]
	s_nop 0
	v_add_f32_e32 v72, v22, v100
	v_add_f32_e32 v72, v72, v101
	v_lshlrev_b32_e32 v100, 16, v69
	v_lshlrev_b32_e32 v101, 16, v73
	v_pk_mov_b32 v[102:103], v[118:119], v[100:101] op_sel:[1,0]
	v_and_b32_e32 v73, 0xffff0000, v73
	v_pk_mul_f32 v[104:105], v[96:97], v[102:103]
	s_nop 0
	v_add_f32_e32 v104, v107, v104
	v_add_f32_e32 v106, v104, v105
	v_pk_mul_f32 v[104:105], v[96:97], v[100:101]
	s_nop 0
	v_add_f32_e32 v72, v72, v104
	v_add_f32_e32 v151, v72, v105
	v_pk_mul_f32 v[104:105], v[14:15], v[88:89]
	s_nop 0
	v_add_f32_e32 v72, v23, v104
	v_add_f32_e32 v107, v72, v105
	v_and_b32_e32 v72, 0xffff0000, v69
	v_pk_mov_b32 v[88:89], v[88:89], v[72:73] op_sel:[1,0]
	s_nop 0
	v_pk_mul_f32 v[104:105], v[18:19], v[88:89]
	s_nop 0
	v_add_f32_e32 v69, v116, v104
	v_add_f32_e32 v69, v69, v105
	v_pk_mul_f32 v[104:105], v[18:19], v[72:73]
	v_cvt_pk_bf16_f32 v69, v106, v69
	s_nop 0
	v_add_f32_e32 v104, v107, v104
	v_add_f32_e32 v152, v104, v105
	v_pk_mul_f32 v[104:105], v[94:95], v[122:123]
	s_nop 0
	v_add_f32_e32 v104, v8, v104
	v_add_f32_e32 v118, v104, v105
	v_lshlrev_b32_e32 v104, 16, v70
	v_lshlrev_b32_e32 v105, 16, v74
	v_pk_mov_b32 v[106:107], v[122:123], v[104:105] op_sel:[1,0]
	s_nop 0
	v_pk_mul_f32 v[116:117], v[98:99], v[106:107]
	s_nop 0
	v_add_f32_e32 v116, v120, v116
	v_add_f32_e32 v122, v116, v117
	v_pk_mul_f32 v[116:117], v[98:99], v[104:105]
	s_nop 0
	v_add_f32_e32 v116, v118, v116
	v_add_f32_e32 v153, v116, v117
	v_pk_mul_f32 v[116:117], v[0:1], v[126:127]
	s_nop 0
	v_add_f32_e32 v116, v9, v116
	v_add_f32_e32 v123, v116, v117
	v_and_b32_e32 v117, 0xffff0000, v74
	v_and_b32_e32 v116, 0xffff0000, v70
	v_pk_mov_b32 v[118:119], v[126:127], v[116:117] op_sel:[1,0]
	s_nop 0
	v_pk_mul_f32 v[120:121], v[4:5], v[118:119]
	s_nop 0
	v_add_f32_e32 v70, v124, v120
	v_add_f32_e32 v70, v70, v121
	v_pk_mul_f32 v[120:121], v[4:5], v[116:117]
	v_cvt_pk_bf16_f32 v70, v122, v70
	s_nop 0
	v_add_f32_e32 v74, v123, v120
	v_add_f32_e32 v154, v74, v121
	v_pk_mul_f32 v[120:121], v[76:77], v[130:131]
	s_nop 0
	v_add_f32_e32 v74, v10, v120
	v_add_f32_e32 v74, v74, v121
	v_lshlrev_b32_e32 v120, 16, v71
	v_lshlrev_b32_e32 v121, 16, v75
	v_pk_mov_b32 v[122:123], v[130:131], v[120:121] op_sel:[1,0]
	v_and_b32_e32 v75, 0xffff0000, v75
	v_pk_mul_f32 v[124:125], v[80:81], v[122:123]
	s_nop 0
	v_add_f32_e32 v124, v128, v124
	v_add_f32_e32 v130, v124, v125
	v_pk_mul_f32 v[124:125], v[80:81], v[120:121]
	s_nop 0
	v_add_f32_e32 v124, v74, v124
	v_and_b32_e32 v74, 0xffff0000, v71
	v_pk_mov_b32 v[126:127], v[90:91], v[74:75] op_sel:[1,0]
	v_pk_mul_f32 v[90:91], v[2:3], v[90:91]
	v_pk_mul_f32 v[128:129], v[6:7], v[126:127]
	v_add_f32_e32 v90, v11, v90
	v_add_f32_e32 v71, v148, v128
	v_add_f32_e32 v71, v71, v129
	v_mov_b32_e32 v128, s0
	v_mov_b32_e32 v129, s1
	v_cvt_pk_bf16_f32 v71, v130, v71
	v_add_f32_e32 v124, v124, v125
	v_readfirstlane_b32 s16, v128
	v_readfirstlane_b32 s17, v129
	s_load_dwordx2 s[16:17], s[16:17], 0xc0
	v_add_f32_e32 v125, v90, v91
	s_waitcnt lgkmcnt(0)
	v_mov_b64_e32 v[90:91], s[16:17]
	v_mad_i64_i32 v[90:91], s[16:17], v147, s24, v[90:91]
	v_lshl_add_u64 v[90:91], v[90:91], 0, v[110:111]
	v_add_co_u32_e32 v90, vcc, s26, v90
	s_nop 1
	v_addc_co_u32_e32 v91, vcc, 0, v91, vcc
	global_store_dwordx4 v[90:91], v[68:71], off
	v_mov_b32_e32 v90, s0
	v_mov_b32_e32 v91, s1
	v_pk_mul_f32 v[68:69], v[6:7], v[74:75]
	s_nop 0
	v_add_f32_e32 v68, v125, v68
	v_add_f32_e32 v71, v68, v69
	v_cvt_pk_bf16_f32 v68, v149, v150
	v_cvt_pk_bf16_f32 v69, v151, v152
	v_cvt_pk_bf16_f32 v70, v153, v154
	v_cvt_pk_bf16_f32 v71, v124, v71
	s_nop 0
	v_readfirstlane_b32 s16, v90
	v_readfirstlane_b32 s17, v91
	s_load_dwordx2 s[16:17], s[16:17], 0xc0
	s_waitcnt lgkmcnt(0)
	v_mov_b64_e32 v[90:91], s[16:17]
	v_mad_i64_i32 v[90:91], s[16:17], v146, s24, v[90:91]
	v_lshl_add_u64 v[90:91], v[90:91], 0, v[110:111]
	v_add_co_u32_e32 v90, vcc, s26, v90
	s_nop 1
	v_addc_co_u32_e32 v91, vcc, 0, v91, vcc
	global_store_dwordx4 v[90:91], v[68:71], off
	s_nop 1
	v_pk_mul_f32 v[68:69], v[112:113], v[78:79]
	s_nop 0
	v_add_f32_e32 v68, v20, v68
	v_add_f32_e32 v90, v68, v69
	v_pk_mul_f32 v[68:69], v[12:13], v[86:87]
	s_nop 0
	v_add_f32_e32 v68, v21, v68
	v_add_f32_e32 v86, v68, v69
	v_pk_mul_f32 v[68:69], v[92:93], v[102:103]
	s_nop 0
	v_add_f32_e32 v68, v22, v68
	v_add_f32_e32 v91, v68, v69
	v_pk_mul_f32 v[68:69], v[14:15], v[88:89]
	s_nop 0
	v_add_f32_e32 v68, v23, v68
	v_add_f32_e32 v102, v68, v69
	v_pk_mul_f32 v[68:69], v[94:95], v[106:107]
	s_nop 0
	v_add_f32_e32 v68, v8, v68
	v_add_f32_e32 v103, v68, v69
	v_pk_mul_f32 v[68:69], v[0:1], v[118:119]
	s_nop 0
	v_add_f32_e32 v68, v9, v68
	v_add_f32_e32 v106, v68, v69
	v_pk_mul_f32 v[68:69], v[76:77], v[122:123]
	s_nop 0
	v_add_f32_e32 v68, v10, v68
	v_add_f32_e32 v118, v68, v69
	v_pk_mul_f32 v[68:69], v[2:3], v[126:127]
	s_nop 0
	v_add_f32_e32 v68, v11, v68
	v_add_f32_e32 v122, v68, v69
	v_pk_mul_f32 v[68:69], v[112:113], v[82:83]
	s_nop 0
	v_add_f32_e32 v68, v20, v68
	v_add_f32_e32 v87, v68, v69
	s_waitcnt vmcnt(15)
	v_lshlrev_b32_e32 v68, 16, v60
	s_waitcnt vmcnt(14)
	v_lshlrev_b32_e32 v69, 16, v64
	v_pk_mov_b32 v[70:71], v[82:83], v[68:69] op_sel:[1,0]
	s_nop 0
	v_pk_mul_f32 v[78:79], v[114:115], v[70:71]
	s_nop 0
	v_add_f32_e32 v78, v90, v78
	v_add_f32_e32 v88, v78, v79
	v_pk_mul_f32 v[78:79], v[114:115], v[68:69]
	s_nop 0
	v_add_f32_e32 v78, v87, v78
	v_add_f32_e32 v123, v78, v79
	v_pk_mul_f32 v[78:79], v[12:13], v[84:85]
	s_nop 0
	v_add_f32_e32 v78, v21, v78
	v_add_f32_e32 v87, v78, v79
	v_and_b32_e32 v79, 0xffff0000, v64
	v_and_b32_e32 v78, 0xffff0000, v60
	v_pk_mov_b32 v[82:83], v[84:85], v[78:79] op_sel:[1,0]
	s_nop 0
	v_pk_mul_f32 v[84:85], v[16:17], v[82:83]
	s_nop 0
	v_add_f32_e32 v60, v86, v84
	v_add_f32_e32 v60, v60, v85
	v_pk_mul_f32 v[84:85], v[16:17], v[78:79]
	v_cvt_pk_bf16_f32 v60, v88, v60
	s_nop 0
	v_add_f32_e32 v64, v87, v84
	v_add_f32_e32 v124, v64, v85
	v_pk_mul_f32 v[84:85], v[92:93], v[100:101]
	s_nop 0
	v_add_f32_e32 v64, v22, v84
	v_add_f32_e32 v64, v64, v85
	v_lshlrev_b32_e32 v84, 16, v61
	v_lshlrev_b32_e32 v85, 16, v65
	v_pk_mov_b32 v[86:87], v[100:101], v[84:85] op_sel:[1,0]
	v_and_b32_e32 v65, 0xffff0000, v65
	v_pk_mul_f32 v[88:89], v[96:97], v[86:87]
	s_nop 0
	v_add_f32_e32 v88, v91, v88
	v_add_f32_e32 v90, v88, v89
	v_pk_mul_f32 v[88:89], v[96:97], v[84:85]
	s_nop 0
	v_add_f32_e32 v64, v64, v88
	v_add_f32_e32 v125, v64, v89
	v_pk_mul_f32 v[88:89], v[14:15], v[72:73]
	s_nop 0
	v_add_f32_e32 v64, v23, v88
	v_add_f32_e32 v91, v64, v89
	v_and_b32_e32 v64, 0xffff0000, v61
	v_pk_mov_b32 v[72:73], v[72:73], v[64:65] op_sel:[1,0]
	s_nop 0
	v_pk_mul_f32 v[88:89], v[18:19], v[72:73]
	s_nop 0
	v_add_f32_e32 v61, v102, v88
	v_add_f32_e32 v61, v61, v89
	v_pk_mul_f32 v[88:89], v[18:19], v[64:65]
	v_cvt_pk_bf16_f32 v61, v90, v61
	s_nop 0
	v_add_f32_e32 v88, v91, v88
	v_add_f32_e32 v126, v88, v89
	v_pk_mul_f32 v[88:89], v[94:95], v[104:105]
	s_nop 0
	v_add_f32_e32 v88, v8, v88
	v_add_f32_e32 v102, v88, v89
	v_lshlrev_b32_e32 v88, 16, v62
	v_lshlrev_b32_e32 v89, 16, v66
	v_pk_mov_b32 v[90:91], v[104:105], v[88:89] op_sel:[1,0]
	s_nop 0
	v_pk_mul_f32 v[100:101], v[98:99], v[90:91]
	s_nop 0
	v_add_f32_e32 v100, v103, v100
	v_add_f32_e32 v107, v100, v101
	v_pk_mul_f32 v[100:101], v[98:99], v[88:89]
	s_nop 0
	v_add_f32_e32 v100, v102, v100
	v_add_f32_e32 v127, v100, v101
	v_pk_mul_f32 v[100:101], v[0:1], v[116:117]
	s_nop 0
	v_add_f32_e32 v100, v9, v100
	v_add_f32_e32 v119, v100, v101
	v_and_b32_e32 v101, 0xffff0000, v66
	v_and_b32_e32 v100, 0xffff0000, v62
	v_pk_mov_b32 v[102:103], v[116:117], v[100:101] op_sel:[1,0]
	s_nop 0
	v_pk_mul_f32 v[104:105], v[4:5], v[102:103]
	s_nop 0
	v_add_f32_e32 v62, v106, v104
	v_add_f32_e32 v62, v62, v105
	v_pk_mul_f32 v[104:105], v[4:5], v[100:101]
	v_cvt_pk_bf16_f32 v62, v107, v62
	s_nop 0
	v_add_f32_e32 v66, v119, v104
	v_add_f32_e32 v128, v66, v105
	v_pk_mul_f32 v[104:105], v[76:77], v[120:121]
	s_nop 0
	v_add_f32_e32 v66, v10, v104
	v_add_f32_e32 v66, v66, v105
	v_lshlrev_b32_e32 v104, 16, v63
	v_lshlrev_b32_e32 v105, 16, v67
	v_pk_mov_b32 v[106:107], v[120:121], v[104:105] op_sel:[1,0]
	v_and_b32_e32 v67, 0xffff0000, v67
	v_pk_mul_f32 v[116:117], v[80:81], v[106:107]
	s_nop 0
	v_add_f32_e32 v116, v118, v116
	v_add_f32_e32 v129, v116, v117
	v_pk_mul_f32 v[116:117], v[80:81], v[104:105]
	s_nop 0
	v_add_f32_e32 v116, v66, v116
	v_and_b32_e32 v66, 0xffff0000, v63
	v_pk_mov_b32 v[118:119], v[74:75], v[66:67] op_sel:[1,0]
	v_pk_mul_f32 v[74:75], v[2:3], v[74:75]
	v_pk_mul_f32 v[120:121], v[6:7], v[118:119]
	v_add_f32_e32 v74, v11, v74
	v_add_f32_e32 v63, v122, v120
	v_add_f32_e32 v63, v63, v121
	v_mov_b32_e32 v120, s0
	v_mov_b32_e32 v121, s1
	v_cvt_pk_bf16_f32 v63, v129, v63
	v_add_f32_e32 v116, v116, v117
	v_readfirstlane_b32 s16, v120
	v_readfirstlane_b32 s17, v121
	s_load_dwordx2 s[16:17], s[16:17], 0xc0
	v_add_f32_e32 v117, v74, v75
	s_waitcnt lgkmcnt(0)
	v_mov_b64_e32 v[74:75], s[16:17]
	v_mad_i64_i32 v[74:75], s[16:17], v145, s24, v[74:75]
	v_lshl_add_u64 v[74:75], v[74:75], 0, v[110:111]
	v_add_co_u32_e32 v74, vcc, s26, v74
	s_nop 1
	v_addc_co_u32_e32 v75, vcc, 0, v75, vcc
	global_store_dwordx4 v[74:75], v[60:63], off
	v_mov_b32_e32 v74, s0
	v_mov_b32_e32 v75, s1
	v_pk_mul_f32 v[60:61], v[6:7], v[66:67]
	s_nop 0
	v_add_f32_e32 v60, v117, v60
	v_add_f32_e32 v63, v60, v61
	v_cvt_pk_bf16_f32 v60, v123, v124
	v_cvt_pk_bf16_f32 v61, v125, v126
	v_cvt_pk_bf16_f32 v62, v127, v128
	v_cvt_pk_bf16_f32 v63, v116, v63
	s_nop 0
	v_readfirstlane_b32 s16, v74
	v_readfirstlane_b32 s17, v75
	s_load_dwordx2 s[16:17], s[16:17], 0xc0
	s_waitcnt lgkmcnt(0)
	v_mov_b64_e32 v[74:75], s[16:17]
	v_mad_i64_i32 v[74:75], s[16:17], v144, s24, v[74:75]
	v_lshl_add_u64 v[74:75], v[74:75], 0, v[110:111]
	v_add_co_u32_e32 v74, vcc, s26, v74
	s_nop 1
	v_addc_co_u32_e32 v75, vcc, 0, v75, vcc
	global_store_dwordx4 v[74:75], v[60:63], off
	s_nop 1
	v_pk_mul_f32 v[60:61], v[112:113], v[70:71]
	s_nop 0
	v_add_f32_e32 v60, v20, v60
	v_add_f32_e32 v70, v60, v61
	v_pk_mul_f32 v[60:61], v[12:13], v[82:83]
	s_nop 0
	v_add_f32_e32 v60, v21, v60
	v_add_f32_e32 v74, v60, v61
	v_pk_mul_f32 v[60:61], v[92:93], v[86:87]
	s_nop 0
	v_add_f32_e32 v60, v22, v60
	v_add_f32_e32 v82, v60, v61
	v_pk_mul_f32 v[60:61], v[14:15], v[72:73]
	s_nop 0
	v_add_f32_e32 v60, v23, v60
	v_add_f32_e32 v83, v60, v61
	v_pk_mul_f32 v[60:61], v[94:95], v[90:91]
	s_nop 0
	v_add_f32_e32 v60, v8, v60
	v_add_f32_e32 v86, v60, v61
	v_pk_mul_f32 v[60:61], v[0:1], v[102:103]
	s_nop 0
	v_add_f32_e32 v60, v9, v60
	v_add_f32_e32 v90, v60, v61
	v_pk_mul_f32 v[60:61], v[76:77], v[106:107]
	s_nop 0
	v_add_f32_e32 v60, v10, v60
	v_add_f32_e32 v102, v60, v61
	v_pk_mul_f32 v[60:61], v[2:3], v[118:119]
	s_nop 0
	v_add_f32_e32 v60, v11, v60
	v_add_f32_e32 v106, v60, v61
	v_pk_mul_f32 v[60:61], v[112:113], v[68:69]
	s_nop 0
	v_add_f32_e32 v60, v20, v60
	v_add_f32_e32 v71, v60, v61
	s_waitcnt vmcnt(15)
	v_lshlrev_b32_e32 v60, 16, v52
	s_waitcnt vmcnt(14)
	v_lshlrev_b32_e32 v61, 16, v56
	v_pk_mov_b32 v[62:63], v[68:69], v[60:61] op_sel:[1,0]
	s_nop 0
	v_pk_mul_f32 v[68:69], v[114:115], v[62:63]
	s_nop 0
	v_add_f32_e32 v68, v70, v68
	v_add_f32_e32 v75, v68, v69
	v_pk_mul_f32 v[68:69], v[114:115], v[60:61]
	s_nop 0
	v_add_f32_e32 v68, v71, v68
	v_add_f32_e32 v107, v68, v69
	v_pk_mul_f32 v[68:69], v[12:13], v[78:79]
	s_nop 0
	v_add_f32_e32 v68, v21, v68
	v_add_f32_e32 v87, v68, v69
	v_and_b32_e32 v69, 0xffff0000, v56
	v_and_b32_e32 v68, 0xffff0000, v52
	v_pk_mov_b32 v[70:71], v[78:79], v[68:69] op_sel:[1,0]
	s_nop 0
	v_pk_mul_f32 v[72:73], v[16:17], v[70:71]
	s_nop 0
	v_add_f32_e32 v52, v74, v72
	v_add_f32_e32 v52, v52, v73
	v_pk_mul_f32 v[72:73], v[16:17], v[68:69]
	v_cvt_pk_bf16_f32 v52, v75, v52
	s_nop 0
	v_add_f32_e32 v56, v87, v72
	v_add_f32_e32 v116, v56, v73
	v_pk_mul_f32 v[72:73], v[92:93], v[84:85]
	s_nop 0
	v_add_f32_e32 v56, v22, v72
	v_add_f32_e32 v56, v56, v73
	v_lshlrev_b32_e32 v72, 16, v53
	v_lshlrev_b32_e32 v73, 16, v57
	v_pk_mov_b32 v[74:75], v[84:85], v[72:73] op_sel:[1,0]
	v_and_b32_e32 v57, 0xffff0000, v57
	v_pk_mul_f32 v[78:79], v[96:97], v[74:75]
	s_nop 0
	v_add_f32_e32 v78, v82, v78
	v_add_f32_e32 v82, v78, v79
	v_pk_mul_f32 v[78:79], v[96:97], v[72:73]
	s_nop 0
	v_add_f32_e32 v56, v56, v78
	v_add_f32_e32 v117, v56, v79
	v_pk_mul_f32 v[78:79], v[14:15], v[64:65]
	s_nop 0
	v_add_f32_e32 v56, v23, v78
	v_add_f32_e32 v84, v56, v79
	v_and_b32_e32 v56, 0xffff0000, v53
	v_pk_mov_b32 v[64:65], v[64:65], v[56:57] op_sel:[1,0]
	s_nop 0
	v_pk_mul_f32 v[78:79], v[18:19], v[64:65]
	s_nop 0
	v_add_f32_e32 v53, v83, v78
	v_add_f32_e32 v53, v53, v79
	v_pk_mul_f32 v[78:79], v[18:19], v[56:57]
	v_cvt_pk_bf16_f32 v53, v82, v53
	s_nop 0
	v_add_f32_e32 v78, v84, v78
	v_add_f32_e32 v118, v78, v79
	v_pk_mul_f32 v[78:79], v[94:95], v[88:89]
	s_nop 0
	v_add_f32_e32 v78, v8, v78
	v_add_f32_e32 v87, v78, v79
	v_lshlrev_b32_e32 v78, 16, v54
	v_lshlrev_b32_e32 v79, 16, v58
	v_pk_mov_b32 v[82:83], v[88:89], v[78:79] op_sel:[1,0]
	s_nop 0
	v_pk_mul_f32 v[84:85], v[98:99], v[82:83]
	s_nop 0
	v_add_f32_e32 v84, v86, v84
	v_add_f32_e32 v91, v84, v85
	v_pk_mul_f32 v[84:85], v[98:99], v[78:79]
	s_nop 0
	v_add_f32_e32 v84, v87, v84
	v_add_f32_e32 v119, v84, v85
	v_pk_mul_f32 v[84:85], v[0:1], v[100:101]
	s_nop 0
	v_add_f32_e32 v84, v9, v84
	v_add_f32_e32 v103, v84, v85
	v_and_b32_e32 v85, 0xffff0000, v58
	v_and_b32_e32 v84, 0xffff0000, v54
	v_pk_mov_b32 v[86:87], v[100:101], v[84:85] op_sel:[1,0]
	s_nop 0
	v_pk_mul_f32 v[88:89], v[4:5], v[86:87]
	s_nop 0
	v_add_f32_e32 v54, v90, v88
	v_add_f32_e32 v54, v54, v89
	v_pk_mul_f32 v[88:89], v[4:5], v[84:85]
	v_cvt_pk_bf16_f32 v54, v91, v54
	s_nop 0
	v_add_f32_e32 v58, v103, v88
	v_add_f32_e32 v120, v58, v89
	v_pk_mul_f32 v[88:89], v[76:77], v[104:105]
	s_nop 0
	v_add_f32_e32 v58, v10, v88
	v_add_f32_e32 v58, v58, v89
	v_lshlrev_b32_e32 v88, 16, v55
	v_lshlrev_b32_e32 v89, 16, v59
	v_pk_mov_b32 v[90:91], v[104:105], v[88:89] op_sel:[1,0]
	v_and_b32_e32 v59, 0xffff0000, v59
	v_pk_mul_f32 v[100:101], v[80:81], v[90:91]
	s_nop 0
	v_add_f32_e32 v100, v102, v100
	v_add_f32_e32 v121, v100, v101
	v_pk_mul_f32 v[100:101], v[80:81], v[88:89]
	s_nop 0
	v_add_f32_e32 v100, v58, v100
	v_and_b32_e32 v58, 0xffff0000, v55
	v_pk_mov_b32 v[102:103], v[66:67], v[58:59] op_sel:[1,0]
	v_pk_mul_f32 v[66:67], v[2:3], v[66:67]
	v_pk_mul_f32 v[104:105], v[6:7], v[102:103]
	v_add_f32_e32 v66, v11, v66
	v_add_f32_e32 v55, v106, v104
	v_add_f32_e32 v55, v55, v105
	v_mov_b32_e32 v104, s0
	v_mov_b32_e32 v105, s1
	v_cvt_pk_bf16_f32 v55, v121, v55
	v_add_f32_e32 v100, v100, v101
	v_readfirstlane_b32 s16, v104
	v_readfirstlane_b32 s17, v105
	s_load_dwordx2 s[16:17], s[16:17], 0xc0
	v_add_f32_e32 v101, v66, v67
	s_waitcnt lgkmcnt(0)
	v_mov_b64_e32 v[66:67], s[16:17]
	v_mad_i64_i32 v[66:67], s[16:17], v143, s24, v[66:67]
	v_lshl_add_u64 v[66:67], v[66:67], 0, v[110:111]
	v_add_co_u32_e32 v66, vcc, s26, v66
	s_nop 1
	v_addc_co_u32_e32 v67, vcc, 0, v67, vcc
	global_store_dwordx4 v[66:67], v[52:55], off
	v_mov_b32_e32 v66, s0
	v_mov_b32_e32 v67, s1
	v_pk_mul_f32 v[52:53], v[6:7], v[58:59]
	s_nop 0
	v_add_f32_e32 v52, v101, v52
	v_add_f32_e32 v55, v52, v53
	v_cvt_pk_bf16_f32 v52, v107, v116
	v_cvt_pk_bf16_f32 v53, v117, v118
	v_cvt_pk_bf16_f32 v54, v119, v120
	v_cvt_pk_bf16_f32 v55, v100, v55
	s_nop 0
	v_readfirstlane_b32 s16, v66
	v_readfirstlane_b32 s17, v67
	s_load_dwordx2 s[16:17], s[16:17], 0xc0
	s_waitcnt lgkmcnt(0)
	v_mov_b64_e32 v[66:67], s[16:17]
	v_mad_i64_i32 v[66:67], s[16:17], v142, s24, v[66:67]
	v_lshl_add_u64 v[66:67], v[66:67], 0, v[110:111]
	v_add_co_u32_e32 v66, vcc, s26, v66
	s_nop 1
	v_addc_co_u32_e32 v67, vcc, 0, v67, vcc
	global_store_dwordx4 v[66:67], v[52:55], off
	s_nop 1
	v_pk_mul_f32 v[52:53], v[112:113], v[62:63]
	s_nop 0
	v_add_f32_e32 v52, v20, v52
	v_add_f32_e32 v62, v52, v53
	v_pk_mul_f32 v[52:53], v[12:13], v[70:71]
	s_nop 0
	v_add_f32_e32 v52, v21, v52
	v_add_f32_e32 v66, v52, v53
	v_pk_mul_f32 v[52:53], v[92:93], v[74:75]
	s_nop 0
	v_add_f32_e32 v52, v22, v52
	v_add_f32_e32 v70, v52, v53
	v_pk_mul_f32 v[52:53], v[14:15], v[64:65]
	s_nop 0
	v_add_f32_e32 v52, v23, v52
	v_add_f32_e32 v71, v52, v53
	v_pk_mul_f32 v[52:53], v[94:95], v[82:83]
	s_nop 0
	v_add_f32_e32 v52, v8, v52
	v_add_f32_e32 v74, v52, v53
	v_pk_mul_f32 v[52:53], v[0:1], v[86:87]
	s_nop 0
	v_add_f32_e32 v52, v9, v52
	v_add_f32_e32 v82, v52, v53
	v_pk_mul_f32 v[52:53], v[76:77], v[90:91]
	s_nop 0
	v_add_f32_e32 v52, v10, v52
	v_add_f32_e32 v86, v52, v53
	v_pk_mul_f32 v[52:53], v[2:3], v[102:103]
	s_nop 0
	v_add_f32_e32 v52, v11, v52
	v_add_f32_e32 v90, v52, v53
	v_pk_mul_f32 v[52:53], v[112:113], v[60:61]
	s_nop 0
	v_add_f32_e32 v52, v20, v52
	v_add_f32_e32 v63, v52, v53
	s_waitcnt vmcnt(15)
	v_lshlrev_b32_e32 v52, 16, v44
	s_waitcnt vmcnt(14)
	v_lshlrev_b32_e32 v53, 16, v48
	v_pk_mov_b32 v[54:55], v[60:61], v[52:53] op_sel:[1,0]
	s_nop 0
	v_pk_mul_f32 v[60:61], v[114:115], v[54:55]
	s_nop 0
	v_add_f32_e32 v60, v62, v60
	v_add_f32_e32 v67, v60, v61
	v_pk_mul_f32 v[60:61], v[114:115], v[52:53]
	s_nop 0
	v_add_f32_e32 v60, v63, v60
	v_add_f32_e32 v91, v60, v61
	v_pk_mul_f32 v[60:61], v[12:13], v[68:69]
	s_nop 0
	v_add_f32_e32 v60, v21, v60
	v_add_f32_e32 v75, v60, v61
	v_and_b32_e32 v61, 0xffff0000, v48
	v_and_b32_e32 v60, 0xffff0000, v44
	v_pk_mov_b32 v[62:63], v[68:69], v[60:61] op_sel:[1,0]
	s_nop 0
	v_pk_mul_f32 v[64:65], v[16:17], v[62:63]
	s_nop 0
	v_add_f32_e32 v44, v66, v64
	v_add_f32_e32 v44, v44, v65
	v_pk_mul_f32 v[64:65], v[16:17], v[60:61]
	v_cvt_pk_bf16_f32 v44, v67, v44
	s_nop 0
	v_add_f32_e32 v48, v75, v64
	v_add_f32_e32 v100, v48, v65
	v_pk_mul_f32 v[64:65], v[92:93], v[72:73]
	s_nop 0
	v_add_f32_e32 v48, v22, v64
	v_add_f32_e32 v48, v48, v65
	v_lshlrev_b32_e32 v64, 16, v45
	v_lshlrev_b32_e32 v65, 16, v49
	v_pk_mov_b32 v[66:67], v[72:73], v[64:65] op_sel:[1,0]
	v_and_b32_e32 v49, 0xffff0000, v49
	v_pk_mul_f32 v[68:69], v[96:97], v[66:67]
	s_nop 0
	v_add_f32_e32 v68, v70, v68
	v_add_f32_e32 v70, v68, v69
	v_pk_mul_f32 v[68:69], v[96:97], v[64:65]
	s_nop 0
	v_add_f32_e32 v48, v48, v68
	v_add_f32_e32 v101, v48, v69
	v_pk_mul_f32 v[68:69], v[14:15], v[56:57]
	s_nop 0
	v_add_f32_e32 v48, v23, v68
	v_add_f32_e32 v72, v48, v69
	v_and_b32_e32 v48, 0xffff0000, v45
	v_pk_mov_b32 v[56:57], v[56:57], v[48:49] op_sel:[1,0]
	s_nop 0
	v_pk_mul_f32 v[68:69], v[18:19], v[56:57]
	s_nop 0
	v_add_f32_e32 v45, v71, v68
	v_add_f32_e32 v45, v45, v69
	v_pk_mul_f32 v[68:69], v[18:19], v[48:49]
	v_cvt_pk_bf16_f32 v45, v70, v45
	s_nop 0
	v_add_f32_e32 v68, v72, v68
	v_add_f32_e32 v102, v68, v69
	v_pk_mul_f32 v[68:69], v[94:95], v[78:79]
	s_nop 0
	v_add_f32_e32 v68, v8, v68
	v_add_f32_e32 v75, v68, v69
	v_lshlrev_b32_e32 v68, 16, v46
	v_lshlrev_b32_e32 v69, 16, v50
	v_pk_mov_b32 v[70:71], v[78:79], v[68:69] op_sel:[1,0]
	s_nop 0
	v_pk_mul_f32 v[72:73], v[98:99], v[70:71]
	s_nop 0
	v_add_f32_e32 v72, v74, v72
	v_add_f32_e32 v83, v72, v73
	v_pk_mul_f32 v[72:73], v[98:99], v[68:69]
	s_nop 0
	v_add_f32_e32 v72, v75, v72
	v_add_f32_e32 v103, v72, v73
	v_pk_mul_f32 v[72:73], v[0:1], v[84:85]
	s_nop 0
	v_add_f32_e32 v72, v9, v72
	v_add_f32_e32 v87, v72, v73
	v_and_b32_e32 v73, 0xffff0000, v50
	v_and_b32_e32 v72, 0xffff0000, v46
	v_pk_mov_b32 v[74:75], v[84:85], v[72:73] op_sel:[1,0]
	s_nop 0
	v_pk_mul_f32 v[78:79], v[4:5], v[74:75]
	s_nop 0
	v_add_f32_e32 v46, v82, v78
	v_add_f32_e32 v46, v46, v79
	v_pk_mul_f32 v[78:79], v[4:5], v[72:73]
	v_cvt_pk_bf16_f32 v46, v83, v46
	s_nop 0
	v_add_f32_e32 v50, v87, v78
	v_add_f32_e32 v104, v50, v79
	v_pk_mul_f32 v[78:79], v[76:77], v[88:89]
	s_nop 0
	v_add_f32_e32 v50, v10, v78
	v_add_f32_e32 v50, v50, v79
	v_lshlrev_b32_e32 v78, 16, v47
	v_lshlrev_b32_e32 v79, 16, v51
	v_pk_mov_b32 v[82:83], v[88:89], v[78:79] op_sel:[1,0]
	v_and_b32_e32 v51, 0xffff0000, v51
	v_pk_mul_f32 v[84:85], v[80:81], v[82:83]
	s_nop 0
	v_add_f32_e32 v84, v86, v84
	v_add_f32_e32 v105, v84, v85
	v_pk_mul_f32 v[84:85], v[80:81], v[78:79]
	s_nop 0
	v_add_f32_e32 v84, v50, v84
	v_and_b32_e32 v50, 0xffff0000, v47
	v_pk_mov_b32 v[86:87], v[58:59], v[50:51] op_sel:[1,0]
	v_pk_mul_f32 v[58:59], v[2:3], v[58:59]
	v_pk_mul_f32 v[88:89], v[6:7], v[86:87]
	v_add_f32_e32 v58, v11, v58
	v_add_f32_e32 v47, v90, v88
	v_add_f32_e32 v47, v47, v89
	v_mov_b32_e32 v88, s0
	v_mov_b32_e32 v89, s1
	v_cvt_pk_bf16_f32 v47, v105, v47
	v_add_f32_e32 v84, v84, v85
	v_readfirstlane_b32 s16, v88
	v_readfirstlane_b32 s17, v89
	s_load_dwordx2 s[16:17], s[16:17], 0xc0
	v_add_f32_e32 v85, v58, v59
	s_waitcnt lgkmcnt(0)
	v_mov_b64_e32 v[58:59], s[16:17]
	v_mad_i64_i32 v[58:59], s[16:17], v141, s24, v[58:59]
	v_lshl_add_u64 v[58:59], v[58:59], 0, v[110:111]
	v_add_co_u32_e32 v58, vcc, s26, v58
	s_nop 1
	v_addc_co_u32_e32 v59, vcc, 0, v59, vcc
	global_store_dwordx4 v[58:59], v[44:47], off
	v_mov_b32_e32 v58, s0
	v_mov_b32_e32 v59, s1
	v_pk_mul_f32 v[44:45], v[6:7], v[50:51]
	s_nop 0
	v_add_f32_e32 v44, v85, v44
	v_add_f32_e32 v47, v44, v45
	v_cvt_pk_bf16_f32 v44, v91, v100
	v_cvt_pk_bf16_f32 v45, v101, v102
	v_cvt_pk_bf16_f32 v46, v103, v104
	v_cvt_pk_bf16_f32 v47, v84, v47
	s_nop 0
	v_readfirstlane_b32 s16, v58
	v_readfirstlane_b32 s17, v59
	s_load_dwordx2 s[16:17], s[16:17], 0xc0
	s_waitcnt lgkmcnt(0)
	v_mov_b64_e32 v[58:59], s[16:17]
	v_mad_i64_i32 v[58:59], s[16:17], v140, s24, v[58:59]
	v_lshl_add_u64 v[58:59], v[58:59], 0, v[110:111]
	v_add_co_u32_e32 v58, vcc, s26, v58
	s_nop 1
	v_addc_co_u32_e32 v59, vcc, 0, v59, vcc
	global_store_dwordx4 v[58:59], v[44:47], off
	s_nop 1
	v_pk_mul_f32 v[44:45], v[112:113], v[54:55]
	s_nop 0
	v_add_f32_e32 v44, v20, v44
	v_add_f32_e32 v54, v44, v45
	v_pk_mul_f32 v[44:45], v[12:13], v[62:63]
	s_nop 0
	v_add_f32_e32 v44, v21, v44
	v_add_f32_e32 v58, v44, v45
	v_pk_mul_f32 v[44:45], v[92:93], v[66:67]
	s_nop 0
	v_add_f32_e32 v44, v22, v44
	v_add_f32_e32 v62, v44, v45
	v_pk_mul_f32 v[44:45], v[14:15], v[56:57]
	s_nop 0
	v_add_f32_e32 v44, v23, v44
	v_add_f32_e32 v63, v44, v45
	v_pk_mul_f32 v[44:45], v[94:95], v[70:71]
	s_nop 0
	v_add_f32_e32 v44, v8, v44
	v_add_f32_e32 v66, v44, v45
	v_pk_mul_f32 v[44:45], v[0:1], v[74:75]
	s_nop 0
	v_add_f32_e32 v44, v9, v44
	v_add_f32_e32 v70, v44, v45
	v_pk_mul_f32 v[44:45], v[76:77], v[82:83]
	s_nop 0
	v_add_f32_e32 v44, v10, v44
	v_add_f32_e32 v74, v44, v45
	v_pk_mul_f32 v[44:45], v[2:3], v[86:87]
	s_nop 0
	v_add_f32_e32 v44, v11, v44
	v_add_f32_e32 v82, v44, v45
	v_pk_mul_f32 v[44:45], v[112:113], v[52:53]
	s_nop 0
	v_add_f32_e32 v44, v20, v44
	v_add_f32_e32 v55, v44, v45
	s_waitcnt vmcnt(15)
	v_lshlrev_b32_e32 v44, 16, v36
	s_waitcnt vmcnt(14)
	v_lshlrev_b32_e32 v45, 16, v40
	v_pk_mov_b32 v[46:47], v[52:53], v[44:45] op_sel:[1,0]
	s_nop 0
	v_pk_mul_f32 v[52:53], v[114:115], v[46:47]
	s_nop 0
	v_add_f32_e32 v52, v54, v52
	v_add_f32_e32 v59, v52, v53
	v_pk_mul_f32 v[52:53], v[114:115], v[44:45]
	s_nop 0
	v_add_f32_e32 v52, v55, v52
	v_add_f32_e32 v83, v52, v53
	v_pk_mul_f32 v[52:53], v[12:13], v[60:61]
	s_nop 0
	v_add_f32_e32 v52, v21, v52
	v_add_f32_e32 v67, v52, v53
	v_and_b32_e32 v53, 0xffff0000, v40
	v_and_b32_e32 v52, 0xffff0000, v36
	v_pk_mov_b32 v[54:55], v[60:61], v[52:53] op_sel:[1,0]
	s_nop 0
	v_pk_mul_f32 v[56:57], v[16:17], v[54:55]
	s_nop 0
	v_add_f32_e32 v36, v58, v56
	v_add_f32_e32 v36, v36, v57
	v_pk_mul_f32 v[56:57], v[16:17], v[52:53]
	v_cvt_pk_bf16_f32 v36, v59, v36
	s_nop 0
	v_add_f32_e32 v40, v67, v56
	v_add_f32_e32 v84, v40, v57
	v_pk_mul_f32 v[56:57], v[92:93], v[64:65]
	s_nop 0
	v_add_f32_e32 v40, v22, v56
	v_add_f32_e32 v40, v40, v57
	v_lshlrev_b32_e32 v56, 16, v37
	v_lshlrev_b32_e32 v57, 16, v41
	v_pk_mov_b32 v[58:59], v[64:65], v[56:57] op_sel:[1,0]
	v_and_b32_e32 v41, 0xffff0000, v41
	v_pk_mul_f32 v[60:61], v[96:97], v[58:59]
	s_nop 0
	v_add_f32_e32 v60, v62, v60
	v_add_f32_e32 v62, v60, v61
	v_pk_mul_f32 v[60:61], v[96:97], v[56:57]
	s_nop 0
	v_add_f32_e32 v40, v40, v60
	v_add_f32_e32 v85, v40, v61
	v_pk_mul_f32 v[60:61], v[14:15], v[48:49]
	s_nop 0
	v_add_f32_e32 v40, v23, v60
	v_add_f32_e32 v64, v40, v61
	v_and_b32_e32 v40, 0xffff0000, v37
	v_pk_mov_b32 v[48:49], v[48:49], v[40:41] op_sel:[1,0]
	s_nop 0
	v_pk_mul_f32 v[60:61], v[18:19], v[48:49]
	s_nop 0
	v_add_f32_e32 v37, v63, v60
	v_add_f32_e32 v37, v37, v61
	v_pk_mul_f32 v[60:61], v[18:19], v[40:41]
	v_cvt_pk_bf16_f32 v37, v62, v37
	s_nop 0
	v_add_f32_e32 v60, v64, v60
	v_add_f32_e32 v86, v60, v61
	v_pk_mul_f32 v[60:61], v[94:95], v[68:69]
	s_nop 0
	v_add_f32_e32 v60, v8, v60
	v_add_f32_e32 v67, v60, v61
	v_lshlrev_b32_e32 v60, 16, v38
	v_lshlrev_b32_e32 v61, 16, v42
	v_pk_mov_b32 v[62:63], v[68:69], v[60:61] op_sel:[1,0]
	s_nop 0
	v_pk_mul_f32 v[64:65], v[98:99], v[62:63]
	s_nop 0
	v_add_f32_e32 v64, v66, v64
	v_add_f32_e32 v71, v64, v65
	v_pk_mul_f32 v[64:65], v[98:99], v[60:61]
	s_nop 0
	v_add_f32_e32 v64, v67, v64
	v_add_f32_e32 v87, v64, v65
	v_pk_mul_f32 v[64:65], v[0:1], v[72:73]
	s_nop 0
	v_add_f32_e32 v64, v9, v64
	v_add_f32_e32 v75, v64, v65
	v_and_b32_e32 v65, 0xffff0000, v42
	v_and_b32_e32 v64, 0xffff0000, v38
	v_pk_mov_b32 v[66:67], v[72:73], v[64:65] op_sel:[1,0]
	s_nop 0
	v_pk_mul_f32 v[68:69], v[4:5], v[66:67]
	s_nop 0
	v_add_f32_e32 v38, v70, v68
	v_add_f32_e32 v38, v38, v69
	v_pk_mul_f32 v[68:69], v[4:5], v[64:65]
	v_cvt_pk_bf16_f32 v38, v71, v38
	s_nop 0
	v_add_f32_e32 v42, v75, v68
	v_add_f32_e32 v88, v42, v69
	v_pk_mul_f32 v[68:69], v[76:77], v[78:79]
	s_nop 0
	v_add_f32_e32 v42, v10, v68
	v_add_f32_e32 v42, v42, v69
	v_lshlrev_b32_e32 v68, 16, v39
	v_lshlrev_b32_e32 v69, 16, v43
	v_pk_mov_b32 v[70:71], v[78:79], v[68:69] op_sel:[1,0]
	v_and_b32_e32 v43, 0xffff0000, v43
	v_pk_mul_f32 v[72:73], v[80:81], v[70:71]
	s_nop 0
	v_add_f32_e32 v72, v74, v72
	v_add_f32_e32 v89, v72, v73
	v_pk_mul_f32 v[72:73], v[80:81], v[68:69]
	s_nop 0
	v_add_f32_e32 v72, v42, v72
	v_and_b32_e32 v42, 0xffff0000, v39
	v_pk_mov_b32 v[74:75], v[50:51], v[42:43] op_sel:[1,0]
	v_pk_mul_f32 v[50:51], v[2:3], v[50:51]
	v_pk_mul_f32 v[78:79], v[6:7], v[74:75]
	v_add_f32_e32 v50, v11, v50
	v_add_f32_e32 v39, v82, v78
	v_add_f32_e32 v39, v39, v79
	v_mov_b32_e32 v78, s0
	v_mov_b32_e32 v79, s1
	v_cvt_pk_bf16_f32 v39, v89, v39
	v_add_f32_e32 v72, v72, v73
	v_readfirstlane_b32 s16, v78
	v_readfirstlane_b32 s17, v79
	s_load_dwordx2 s[16:17], s[16:17], 0xc0
	v_add_f32_e32 v73, v50, v51
	s_waitcnt lgkmcnt(0)
	v_mov_b64_e32 v[50:51], s[16:17]
	v_mad_i64_i32 v[50:51], s[16:17], v139, s24, v[50:51]
	v_lshl_add_u64 v[50:51], v[50:51], 0, v[110:111]
	v_add_co_u32_e32 v50, vcc, s26, v50
	s_nop 1
	v_addc_co_u32_e32 v51, vcc, 0, v51, vcc
	global_store_dwordx4 v[50:51], v[36:39], off
	v_mov_b32_e32 v50, s0
	v_mov_b32_e32 v51, s1
	v_pk_mul_f32 v[36:37], v[6:7], v[42:43]
	s_nop 0
	v_add_f32_e32 v36, v73, v36
	v_add_f32_e32 v39, v36, v37
	v_cvt_pk_bf16_f32 v36, v83, v84
	v_cvt_pk_bf16_f32 v37, v85, v86
	v_cvt_pk_bf16_f32 v38, v87, v88
	v_cvt_pk_bf16_f32 v39, v72, v39
	s_nop 0
	v_readfirstlane_b32 s16, v50
	v_readfirstlane_b32 s17, v51
	s_load_dwordx2 s[16:17], s[16:17], 0xc0
	s_waitcnt lgkmcnt(0)
	v_mov_b64_e32 v[50:51], s[16:17]
	v_mad_i64_i32 v[50:51], s[16:17], v138, s24, v[50:51]
	v_lshl_add_u64 v[50:51], v[50:51], 0, v[110:111]
	v_add_co_u32_e32 v50, vcc, s26, v50
	s_nop 1
	v_addc_co_u32_e32 v51, vcc, 0, v51, vcc
	global_store_dwordx4 v[50:51], v[36:39], off
	s_nop 1
	v_pk_mul_f32 v[36:37], v[112:113], v[46:47]
	s_nop 0
	v_add_f32_e32 v36, v20, v36
	v_add_f32_e32 v46, v36, v37
	v_pk_mul_f32 v[36:37], v[12:13], v[54:55]
	s_nop 0
	v_add_f32_e32 v36, v21, v36
	v_add_f32_e32 v50, v36, v37
	v_pk_mul_f32 v[36:37], v[92:93], v[58:59]
	s_nop 0
	v_add_f32_e32 v36, v22, v36
	v_add_f32_e32 v54, v36, v37
	v_pk_mul_f32 v[36:37], v[14:15], v[48:49]
	s_nop 0
	v_add_f32_e32 v36, v23, v36
	v_add_f32_e32 v55, v36, v37
	v_pk_mul_f32 v[36:37], v[94:95], v[62:63]
	s_nop 0
	v_add_f32_e32 v36, v8, v36
	v_add_f32_e32 v58, v36, v37
	v_pk_mul_f32 v[36:37], v[0:1], v[66:67]
	s_nop 0
	v_add_f32_e32 v36, v9, v36
	v_add_f32_e32 v62, v36, v37
	v_pk_mul_f32 v[36:37], v[76:77], v[70:71]
	s_nop 0
	v_add_f32_e32 v36, v10, v36
	v_add_f32_e32 v66, v36, v37
	v_pk_mul_f32 v[36:37], v[2:3], v[74:75]
	s_nop 0
	v_add_f32_e32 v36, v11, v36
	v_add_f32_e32 v70, v36, v37
	v_pk_mul_f32 v[36:37], v[112:113], v[44:45]
	s_nop 0
	v_add_f32_e32 v36, v20, v36
	v_add_f32_e32 v47, v36, v37
	s_waitcnt vmcnt(15)
	v_lshlrev_b32_e32 v36, 16, v28
	s_waitcnt vmcnt(14)
	v_lshlrev_b32_e32 v37, 16, v32
	v_pk_mov_b32 v[38:39], v[44:45], v[36:37] op_sel:[1,0]
	s_nop 0
	v_pk_mul_f32 v[44:45], v[114:115], v[38:39]
	v_pk_mul_f32 v[38:39], v[112:113], v[38:39]
	v_add_f32_e32 v44, v46, v44
	v_add_f32_e32 v51, v44, v45
	v_pk_mul_f32 v[44:45], v[114:115], v[36:37]
	v_add_f32_e32 v20, v20, v38
	v_add_f32_e32 v36, v47, v44
	v_add_f32_e32 v36, v36, v45
	v_pk_mul_f32 v[44:45], v[12:13], v[52:53]
	v_add_f32_e32 v20, v20, v39
	v_add_f32_e32 v44, v21, v44
	v_add_f32_e32 v59, v44, v45
	v_and_b32_e32 v45, 0xffff0000, v32
	v_and_b32_e32 v44, 0xffff0000, v28
	v_pk_mov_b32 v[46:47], v[52:53], v[44:45] op_sel:[1,0]
	s_nop 0
	v_pk_mul_f32 v[48:49], v[16:17], v[46:47]
	v_pk_mul_f32 v[12:13], v[12:13], v[46:47]
	v_add_f32_e32 v28, v50, v48
	v_add_f32_e32 v28, v28, v49
	v_pk_mul_f32 v[48:49], v[16:17], v[44:45]
	v_cvt_pk_bf16_f32 v28, v51, v28
	v_add_f32_e32 v12, v21, v12
	v_add_f32_e32 v32, v59, v48
	v_add_f32_e32 v44, v32, v49
	v_pk_mul_f32 v[48:49], v[92:93], v[56:57]
	v_add_f32_e32 v21, v12, v13
	v_add_f32_e32 v32, v22, v48
	v_add_f32_e32 v32, v32, v49
	v_lshlrev_b32_e32 v48, 16, v29
	v_lshlrev_b32_e32 v49, 16, v33
	v_pk_mov_b32 v[50:51], v[56:57], v[48:49] op_sel:[1,0]
	v_and_b32_e32 v33, 0xffff0000, v33
	v_pk_mul_f32 v[52:53], v[96:97], v[50:51]
	s_nop 0
	v_add_f32_e32 v52, v54, v52
	v_add_f32_e32 v54, v52, v53
	v_pk_mul_f32 v[52:53], v[96:97], v[48:49]
	s_nop 0
	v_add_f32_e32 v32, v32, v52
	v_add_f32_e32 v48, v32, v53
	v_pk_mul_f32 v[52:53], v[14:15], v[40:41]
	s_nop 0
	v_add_f32_e32 v32, v23, v52
	v_add_f32_e32 v56, v32, v53
	v_and_b32_e32 v32, 0xffff0000, v29
	v_pk_mov_b32 v[40:41], v[40:41], v[32:33] op_sel:[1,0]
	s_nop 0
	v_pk_mul_f32 v[52:53], v[18:19], v[40:41]
	s_nop 0
	v_add_f32_e32 v29, v55, v52
	v_add_f32_e32 v29, v29, v53
	v_pk_mul_f32 v[52:53], v[18:19], v[32:33]
	v_cvt_pk_bf16_f32 v29, v54, v29
	s_nop 0
	v_add_f32_e32 v32, v56, v52
	v_add_f32_e32 v32, v32, v53
	v_pk_mul_f32 v[52:53], v[94:95], v[60:61]
	s_nop 0
	v_add_f32_e32 v52, v8, v52
	v_add_f32_e32 v59, v52, v53
	v_lshlrev_b32_e32 v52, 16, v30
	v_lshlrev_b32_e32 v53, 16, v34
	v_pk_mov_b32 v[54:55], v[60:61], v[52:53] op_sel:[1,0]
	s_nop 0
	v_pk_mul_f32 v[56:57], v[98:99], v[54:55]
	s_nop 0
	v_add_f32_e32 v56, v58, v56
	v_add_f32_e32 v63, v56, v57
	v_pk_mul_f32 v[56:57], v[98:99], v[52:53]
	s_nop 0
	v_add_f32_e32 v52, v59, v56
	v_add_f32_e32 v52, v52, v57
	v_pk_mul_f32 v[56:57], v[0:1], v[64:65]
	s_nop 0
	v_add_f32_e32 v56, v9, v56
	v_add_f32_e32 v67, v56, v57
	v_and_b32_e32 v57, 0xffff0000, v34
	v_and_b32_e32 v56, 0xffff0000, v30
	v_pk_mov_b32 v[58:59], v[64:65], v[56:57] op_sel:[1,0]
	s_nop 0
	v_pk_mul_f32 v[60:61], v[4:5], v[58:59]
	v_pk_mul_f32 v[0:1], v[0:1], v[58:59]
	v_add_f32_e32 v30, v62, v60
	v_add_f32_e32 v30, v30, v61
	v_pk_mul_f32 v[60:61], v[4:5], v[56:57]
	v_cvt_pk_bf16_f32 v30, v63, v30
	v_add_f32_e32 v0, v9, v0
	v_add_f32_e32 v34, v67, v60
	v_add_f32_e32 v56, v34, v61
	v_pk_mul_f32 v[60:61], v[76:77], v[68:69]
	v_add_f32_e32 v9, v0, v1
	v_add_f32_e32 v34, v10, v60
	v_add_f32_e32 v34, v34, v61
	v_lshlrev_b32_e32 v60, 16, v31
	v_lshlrev_b32_e32 v61, 16, v35
	v_pk_mov_b32 v[62:63], v[68:69], v[60:61] op_sel:[1,0]
	v_and_b32_e32 v35, 0xffff0000, v35
	v_pk_mul_f32 v[64:65], v[80:81], v[62:63]
	s_nop 0
	v_add_f32_e32 v64, v66, v64
	v_add_f32_e32 v71, v64, v65
	v_pk_mul_f32 v[64:65], v[80:81], v[60:61]
	s_nop 0
	v_add_f32_e32 v60, v34, v64
	v_and_b32_e32 v34, 0xffff0000, v31
	v_pk_mov_b32 v[66:67], v[42:43], v[34:35] op_sel:[1,0]
	v_mov_b32_e32 v64, s0
	v_pk_mul_f32 v[68:69], v[6:7], v[66:67]
	v_pk_mul_f32 v[42:43], v[2:3], v[42:43]
	v_add_f32_e32 v31, v70, v68
	v_add_f32_e32 v31, v31, v69
	v_mov_b32_e32 v68, s1
	v_cvt_pk_bf16_f32 v31, v71, v31
	v_add_f32_e32 v42, v11, v42
	v_readfirstlane_b32 s16, v64
	v_readfirstlane_b32 s17, v68
	s_load_dwordx2 s[16:17], s[16:17], 0xc0
	v_add_f32_e32 v64, v42, v43
	v_add_f32_e32 v60, v60, v65
	s_waitcnt vmcnt(13)
	v_and_b32_e32 v69, 0xffff0000, v26
	v_mov_b32_e32 v68, v57
	s_waitcnt lgkmcnt(0)
	v_mov_b64_e32 v[42:43], s[16:17]
	v_mad_i64_i32 v[42:43], s[16:17], v137, s24, v[42:43]
	v_lshl_add_u64 v[42:43], v[42:43], 0, v[110:111]
	v_add_co_u32_e32 v42, vcc, s26, v42
	v_pk_mul_f32 v[0:1], v[4:5], v[68:69]
	s_nop 0
	v_addc_co_u32_e32 v43, vcc, 0, v43, vcc
	global_store_dwordx4 v[42:43], v[28:31], off
	v_add_f32_e32 v0, v9, v0
	v_add_f32_e32 v4, v0, v1
	v_pk_mul_f32 v[28:29], v[6:7], v[34:35]
	v_mov_b32_e32 v34, s1
	v_add_f32_e32 v28, v64, v28
	v_add_f32_e32 v31, v28, v29
	v_cvt_pk_bf16_f32 v28, v36, v44
	v_cvt_pk_bf16_f32 v29, v48, v32
	v_mov_b32_e32 v32, s0
	v_cvt_pk_bf16_f32 v30, v52, v56
	v_cvt_pk_bf16_f32 v31, v60, v31
	v_pk_mul_f32 v[0:1], v[76:77], v[62:63]
	v_readfirstlane_b32 s16, v32
	v_readfirstlane_b32 s17, v34
	s_load_dwordx2 s[16:17], s[16:17], 0xc0
	v_lshlrev_b32_e32 v71, 16, v27
	v_add_f32_e32 v0, v10, v0
	v_mov_b32_e32 v70, v61
	v_add_f32_e32 v5, v0, v1
	s_waitcnt lgkmcnt(0)
	v_mov_b64_e32 v[42:43], s[16:17]
	v_mad_i64_i32 v[42:43], s[16:17], v136, s24, v[42:43]
	v_lshl_add_u64 v[42:43], v[42:43], 0, v[110:111]
	v_add_co_u32_e32 v42, vcc, s26, v42
	v_pk_mul_f32 v[0:1], v[80:81], v[70:71]
	s_nop 0
	v_addc_co_u32_e32 v43, vcc, 0, v43, vcc
	global_store_dwordx4 v[42:43], v[28:31], off
	v_lshlrev_b32_e32 v43, 16, v25
	v_mov_b32_e32 v42, v49
	v_and_b32_e32 v31, 0xffff0000, v24
	v_mov_b32_e32 v30, v45
	v_pk_mul_f32 v[12:13], v[16:17], v[30:31]
	v_lshlrev_b32_e32 v29, 16, v24
	v_add_f32_e32 v12, v21, v12
	v_add_f32_e32 v16, v12, v13
	v_pk_mul_f32 v[12:13], v[92:93], v[50:51]
	v_and_b32_e32 v25, 0xffff0000, v25
	v_add_f32_e32 v12, v22, v12
	v_add_f32_e32 v17, v12, v13
	v_pk_mul_f32 v[12:13], v[96:97], v[42:43]
	v_mov_b32_e32 v24, v33
	v_add_f32_e32 v12, v17, v12
	v_add_f32_e32 v17, v12, v13
	v_pk_mul_f32 v[12:13], v[14:15], v[40:41]
	v_add_f32_e32 v0, v5, v0
	v_add_f32_e32 v12, v23, v12
	v_add_f32_e32 v14, v12, v13
	v_pk_mul_f32 v[12:13], v[18:19], v[24:25]
	v_add_f32_e32 v5, v0, v1
	v_add_f32_e32 v12, v14, v12
	v_pk_mul_f32 v[0:1], v[2:3], v[66:67]
	v_lshlrev_b32_e32 v65, 16, v26
	v_and_b32_e32 v27, 0xffff0000, v27
	v_add_f32_e32 v14, v12, v13
	v_pk_mul_f32 v[12:13], v[94:95], v[54:55]
	v_add_f32_e32 v0, v11, v0
	v_mov_b32_e32 v26, v35
	v_mov_b32_e32 v28, v37
	v_add_f32_e32 v8, v8, v12
	v_mov_b32_e32 v64, v53
	v_add_f32_e32 v2, v0, v1
	v_pk_mul_f32 v[0:1], v[6:7], v[26:27]
	v_pk_mul_f32 v[28:29], v[114:115], v[28:29]
	v_add_f32_e32 v8, v8, v13
	v_pk_mul_f32 v[12:13], v[98:99], v[64:65]
	v_add_f32_e32 v0, v2, v0
	v_add_f32_e32 v20, v20, v28
	v_add_f32_e32 v8, v8, v12
	v_add_f32_e32 v3, v0, v1
	v_add_f32_e32 v20, v20, v29
	v_add_f32_e32 v8, v8, v13
	v_cvt_pk_bf16_f32 v0, v20, v16
	v_cvt_pk_bf16_f32 v1, v17, v14
	v_cvt_pk_bf16_f32 v2, v8, v4
	v_cvt_pk_bf16_f32 v3, v5, v3
	s_nop 0
	v_readfirstlane_b32 s16, v133
	v_readfirstlane_b32 s17, v134
	s_load_dwordx2 s[16:17], s[16:17], 0xc0
	s_waitcnt lgkmcnt(0)
	v_mov_b64_e32 v[4:5], s[16:17]
	v_mad_i64_i32 v[4:5], s[16:17], v135, s24, v[4:5]
	v_lshl_add_u64 v[4:5], v[4:5], 0, v[110:111]
	v_add_co_u32_e32 v4, vcc, 0x14000000, v4
	s_nop 1
	v_addc_co_u32_e32 v5, vcc, 0, v5, vcc
	v_cmp_lt_i32_e32 vcc, s27, v109
	s_or_b64 s[10:11], vcc, s[10:11]
	global_store_dwordx4 v[4:5], v[0:3], off
	s_andn2_b64 exec, exec, s[10:11]
	s_cbranch_execz .LBB0_487
